# GEMM phases 7/8/10: blocks that own one more tile than their CU partner skip the s_setprio 0 between MFMA groups (stay at priority 1), so both blocks of a CU finish together
# baseline (speedup 1.0000x reference)
.LBB0_951:
	s_cmp_lt_i32 s92, 8
	s_cselect_b64 s[0:1], -1, 0
	s_cmp_gt_i32 s93, 7
	s_cselect_b64 s[4:5], -1, 0
	s_and_b64 s[0:1], s[0:1], s[4:5]
	s_andn2_b64 vcc, exec, s[0:1]
	s_cbranch_vccnz .LBB0_1030
	s_and_b32 s34, s2, 4
	s_cmp_eq_u32 s34, 0
	s_cselect_b32 s34, 1, 0
	s_cmp_lt_u32 s2, 64
	s_cselect_b32 s34, s34, 0
	s_and_b32 s3, s2, 7
	s_sub_i32 s0, 0x8b, s3
	s_lshr_b32 s10, s2, 3
	s_and_b32 s11, s0, 0x88
	s_cmp_ge_u32 s10, s11
	s_cbranch_scc1 .LBB0_971
	v_lshrrev_b32_e32 v1, 2, v218
	v_lshrrev_b32_e32 v0, 1, v218
	v_and_b32_e32 v1, 12, v1
	s_movk_i32 s0, 0x1c0
	v_and_or_b32 v0, v0, s0, v1
	v_and_b32_e32 v1, 0x4f, v218
	v_and_b32_e32 v2, 16, v218
	v_and_b32_e32 v3, 0x5f, v218
	s_waitcnt vmcnt(25)
	v_bitop3_b32 v4, v1, v218, 16 bitop3:0x72
	v_bitop3_b32 v1, v1, v2, 48 bitop3:0x36
	v_lshlrev_b32_e32 v3, 2, v3
	v_lshlrev_b32_e32 v0, 9, v0
	v_lshlrev_b32_e32 v4, 2, v4
	v_lshlrev_b32_e32 v1, 2, v1
	s_waitcnt vmcnt(7)
	v_add_u32_e32 v170, v3, v0
	v_add_u32_e32 v171, v4, v0
	v_add_u32_e32 v172, v1, v0
	v_mbcnt_lo_u32_b32 v0, -1, 0
	s_lshr_b32 s12, s94, 3
	s_lshl_b32 s13, s3, 7
	s_mov_b32 s5, 0
	v_mov_b32_e32 v129, 0
	s_mov_b32 s14, 0x7ffffc0
	s_movk_i32 s15, 0xa0
	s_mov_b64 s[6:7], 0x100
	s_movk_i32 s16, 0x4000
	v_mbcnt_hi_u32_b32 v173, -1, v0
	s_mov_b32 s9, s10
	s_mov_b32 s17, 0
	s_branch .LBB0_955

.LBB0_956:
	ds_read_b128 v[154:157], v131
	ds_read_b128 v[158:161], v131 offset:2560
	ds_read_b128 v[162:165], v131 offset:5120
	ds_read_b128 v[166:169], v131 offset:7680
	ds_read_b128 v[174:177], v133 offset:20480
	ds_read_b128 v[178:181], v133 offset:23040
	ds_read_b128 v[182:185], v133 offset:25600
	ds_read_b128 v[186:189], v133 offset:28160
	s_addk_i32 s9, 0x80
	s_setprio 1
	s_waitcnt lgkmcnt(3)
	v_mfma_f32_16x16x32_bf16 v[64:67], v[154:157], v[174:177], v[64:67]
	s_waitcnt lgkmcnt(2)
	v_mfma_f32_16x16x32_bf16 v[68:71], v[154:157], v[178:181], v[68:71]
	s_waitcnt lgkmcnt(1)
	v_mfma_f32_16x16x32_bf16 v[72:75], v[154:157], v[182:185], v[72:75]
	s_waitcnt lgkmcnt(0)
	v_mfma_f32_16x16x32_bf16 v[76:79], v[154:157], v[186:189], v[76:79]
	v_mfma_f32_16x16x32_bf16 v[80:83], v[158:161], v[174:177], v[80:83]
	v_mfma_f32_16x16x32_bf16 v[84:87], v[158:161], v[178:181], v[84:87]
	v_mfma_f32_16x16x32_bf16 v[88:91], v[158:161], v[182:185], v[88:91]
	v_mfma_f32_16x16x32_bf16 v[92:95], v[158:161], v[186:189], v[92:95]
	v_mfma_f32_16x16x32_bf16 v[154:157], v[162:165], v[174:177], v[96:99]
	v_mfma_f32_16x16x32_bf16 v[158:161], v[162:165], v[178:181], v[100:103]
	v_mfma_f32_16x16x32_bf16 v[190:193], v[162:165], v[182:185], v[104:107]
	v_mfma_f32_16x16x32_bf16 v[162:165], v[162:165], v[186:189], v[108:111]
	v_mfma_f32_16x16x32_bf16 v[174:177], v[166:169], v[174:177], v[112:115]
	v_mfma_f32_16x16x32_bf16 v[178:181], v[166:169], v[178:181], v[116:119]
	v_mfma_f32_16x16x32_bf16 v[182:185], v[166:169], v[182:185], v[120:123]
	v_mfma_f32_16x16x32_bf16 v[166:169], v[166:169], v[186:189], v[124:127]
	s_cmp_lg_u32 s34, 0
	s_cbranch_scc1 .Lfv_0
	s_setprio 0
.Lfv_0:
	ds_read_b128 v[96:99], v131 offset:64
	ds_read_b128 v[186:189], v131 offset:2624
	ds_read_b128 v[194:197], v131 offset:5184
	ds_read_b128 v[198:201], v131 offset:7744
	ds_read_b128 v[202:205], v133 offset:20544
	ds_read_b128 v[206:209], v133 offset:23104
	ds_read_b128 v[210:213], v133 offset:25664
	ds_read_b128 v[220:223], v133 offset:28224
	s_setprio 1
	s_waitcnt lgkmcnt(3)
	v_mfma_f32_16x16x32_bf16 v[124:127], v[96:99], v[202:205], v[64:67]
	s_waitcnt lgkmcnt(2)
	v_mfma_f32_16x16x32_bf16 v[120:123], v[96:99], v[206:209], v[68:71]
	s_waitcnt lgkmcnt(1)
	v_mfma_f32_16x16x32_bf16 v[116:119], v[96:99], v[210:213], v[72:75]
	s_waitcnt lgkmcnt(0)
	v_mfma_f32_16x16x32_bf16 v[112:115], v[96:99], v[220:223], v[76:79]
	v_mfma_f32_16x16x32_bf16 v[108:111], v[186:189], v[202:205], v[80:83]
	v_mfma_f32_16x16x32_bf16 v[104:107], v[186:189], v[206:209], v[84:87]
	v_mfma_f32_16x16x32_bf16 v[100:103], v[186:189], v[210:213], v[88:91]
	v_mfma_f32_16x16x32_bf16 v[96:99], v[186:189], v[220:223], v[92:95]
	v_mfma_f32_16x16x32_bf16 v[92:95], v[194:197], v[202:205], v[154:157]
	v_mfma_f32_16x16x32_bf16 v[88:91], v[194:197], v[206:209], v[158:161]
	v_mfma_f32_16x16x32_bf16 v[84:87], v[194:197], v[210:213], v[190:193]
	v_mfma_f32_16x16x32_bf16 v[80:83], v[194:197], v[220:223], v[162:165]
	v_mfma_f32_16x16x32_bf16 v[76:79], v[198:201], v[202:205], v[174:177]
	v_mfma_f32_16x16x32_bf16 v[72:75], v[198:201], v[206:209], v[178:181]
	v_mfma_f32_16x16x32_bf16 v[68:71], v[198:201], v[210:213], v[182:185]
	v_mfma_f32_16x16x32_bf16 v[64:67], v[198:201], v[220:223], v[166:169]
	s_cmp_lg_u32 s34, 0
	s_cbranch_scc1 .Lfv_1
	s_setprio 0
.Lfv_1:
	v_lshl_add_u64 v[138:139], v[138:139], 0, s[6:7]
	v_lshl_add_u64 v[140:141], v[140:141], 0, s[6:7]
	v_lshl_add_u64 v[142:143], v[142:143], 0, s[6:7]
	v_lshl_add_u64 v[144:145], v[144:145], 0, s[6:7]
	v_lshl_add_u64 v[146:147], v[146:147], 0, s[6:7]
	v_lshl_add_u64 v[148:149], v[148:149], 0, s[6:7]
	v_lshl_add_u64 v[150:151], v[150:151], 0, s[6:7]
	s_andn2_b64 vcc, exec, s[0:1]
	v_lshl_add_u64 v[152:153], v[152:153], 0, s[6:7]
	s_cbranch_vccz .LBB0_961

.LBB0_959:
	ds_read_b128 v[174:177], v131
	ds_read_b128 v[178:181], v131 offset:2560
	ds_read_b128 v[182:185], v131 offset:5120
	ds_read_b128 v[186:189], v131 offset:7680
	ds_read_b128 v[190:193], v133 offset:20480
	ds_read_b128 v[194:197], v133 offset:23040
	ds_read_b128 v[198:201], v133 offset:25600
	ds_read_b128 v[202:205], v133 offset:28160
	s_setprio 1
	s_waitcnt lgkmcnt(3)
	v_mfma_f32_16x16x32_bf16 v[124:127], v[174:177], v[190:193], v[124:127]
	s_waitcnt lgkmcnt(2)
	v_mfma_f32_16x16x32_bf16 v[120:123], v[174:177], v[194:197], v[120:123]
	s_waitcnt lgkmcnt(1)
	v_mfma_f32_16x16x32_bf16 v[116:119], v[174:177], v[198:201], v[116:119]
	s_waitcnt lgkmcnt(0)
	v_mfma_f32_16x16x32_bf16 v[112:115], v[174:177], v[202:205], v[112:115]
	v_mfma_f32_16x16x32_bf16 v[108:111], v[178:181], v[190:193], v[108:111]
	v_mfma_f32_16x16x32_bf16 v[104:107], v[178:181], v[194:197], v[104:107]
	v_mfma_f32_16x16x32_bf16 v[100:103], v[178:181], v[198:201], v[100:103]
	v_mfma_f32_16x16x32_bf16 v[96:99], v[178:181], v[202:205], v[96:99]
	v_mfma_f32_16x16x32_bf16 v[174:177], v[182:185], v[190:193], v[92:95]
	v_mfma_f32_16x16x32_bf16 v[178:181], v[182:185], v[194:197], v[88:91]
	v_mfma_f32_16x16x32_bf16 v[206:209], v[182:185], v[198:201], v[84:87]
	v_mfma_f32_16x16x32_bf16 v[182:185], v[182:185], v[202:205], v[80:83]
	v_mfma_f32_16x16x32_bf16 v[190:193], v[186:189], v[190:193], v[76:79]
	v_mfma_f32_16x16x32_bf16 v[194:197], v[186:189], v[194:197], v[72:75]
	v_mfma_f32_16x16x32_bf16 v[198:201], v[186:189], v[198:201], v[68:71]
	v_mfma_f32_16x16x32_bf16 v[186:189], v[186:189], v[202:205], v[64:67]
	s_cmp_lg_u32 s34, 0
	s_cbranch_scc1 .Lfv_2
	s_setprio 0
.Lfv_2:
	ds_read_b128 v[76:79], v131 offset:64
	ds_read_b128 v[92:95], v131 offset:2624
	ds_read_b128 v[202:205], v131 offset:5184
	ds_read_b128 v[210:213], v131 offset:7744
	ds_read_b128 v[220:223], v133 offset:20544
	ds_read_b128 v[224:227], v133 offset:23104
	ds_read_b128 v[228:231], v133 offset:25664
	ds_read_b128 v[232:235], v133 offset:28224
	s_setprio 1
	s_waitcnt lgkmcnt(3)
	v_mfma_f32_16x16x32_bf16 v[64:67], v[76:79], v[220:223], v[124:127]
	s_waitcnt lgkmcnt(2)
	v_mfma_f32_16x16x32_bf16 v[68:71], v[76:79], v[224:227], v[120:123]
	s_waitcnt lgkmcnt(1)
	v_mfma_f32_16x16x32_bf16 v[72:75], v[76:79], v[228:231], v[116:119]
	s_waitcnt lgkmcnt(0)
	v_mfma_f32_16x16x32_bf16 v[76:79], v[76:79], v[232:235], v[112:115]
	v_mfma_f32_16x16x32_bf16 v[80:83], v[92:95], v[220:223], v[108:111]
	v_mfma_f32_16x16x32_bf16 v[84:87], v[92:95], v[224:227], v[104:107]
	v_mfma_f32_16x16x32_bf16 v[88:91], v[92:95], v[228:231], v[100:103]
	v_mfma_f32_16x16x32_bf16 v[92:95], v[92:95], v[232:235], v[96:99]
	v_mfma_f32_16x16x32_bf16 v[96:99], v[202:205], v[220:223], v[174:177]
	v_mfma_f32_16x16x32_bf16 v[100:103], v[202:205], v[224:227], v[178:181]
	v_mfma_f32_16x16x32_bf16 v[104:107], v[202:205], v[228:231], v[206:209]
	v_mfma_f32_16x16x32_bf16 v[108:111], v[202:205], v[232:235], v[182:185]
	v_mfma_f32_16x16x32_bf16 v[112:115], v[210:213], v[220:223], v[190:193]
	v_mfma_f32_16x16x32_bf16 v[116:119], v[210:213], v[224:227], v[194:197]
	v_mfma_f32_16x16x32_bf16 v[120:123], v[210:213], v[228:231], v[198:201]
	v_mfma_f32_16x16x32_bf16 v[124:127], v[210:213], v[232:235], v[186:189]
	s_cmp_lg_u32 s34, 0
	s_cbranch_scc1 .Lfv_3
	s_setprio 0
.Lfv_3:
	s_cmpk_gt_u32 s9, 0x33f
	s_barrier
	ds_write_b128 v130, v[4:7]
	ds_write_b128 v130, v[12:15] offset:20480
	ds_write_b128 v132, v[20:23]
	ds_write_b128 v132, v[28:31] offset:20480
	ds_write_b128 v134, v[36:39]
	ds_write_b128 v134, v[44:47] offset:20480
	ds_write_b128 v136, v[52:55]
	s_waitcnt vmcnt(0)
	ds_write_b128 v136, v[60:63] offset:20480
	s_waitcnt lgkmcnt(0)
	s_barrier
	s_cbranch_scc1 .LBB0_956
	global_load_dwordx4 v[4:7], v[168:169], off offset:384
	global_load_dwordx4 v[12:15], v[166:167], off offset:384
	global_load_dwordx4 v[20:23], v[164:165], off offset:384
	global_load_dwordx4 v[28:31], v[162:163], off offset:384
	global_load_dwordx4 v[36:39], v[160:161], off offset:384
	global_load_dwordx4 v[44:47], v[158:159], off offset:384
	global_load_dwordx4 v[52:55], v[156:157], off offset:384
	global_load_dwordx4 v[60:63], v[154:155], off offset:384
	s_branch .LBB0_956

.LBB0_1030:
	s_setprio 0
	s_cmp_lt_i32 s92, 9
	s_cselect_b64 s[0:1], -1, 0
	s_cmp_gt_i32 s93, 8
	s_cselect_b64 s[4:5], -1, 0
	s_and_b64 s[0:1], s[0:1], s[4:5]
	s_andn2_b64 vcc, exec, s[0:1]
	s_cbranch_vccnz .LBB0_1113
	s_and_b32 s34, s2, 4
	s_cmp_eq_u32 s34, 0
	s_cselect_b32 s34, 1, 0
	s_cmp_lt_u32 s2, 128
	s_cselect_b32 s34, s34, 0
	s_and_b32 s0, s2, 7
	s_sub_i32 s1, 0x8b, s0
	s_lshl_b32 s4, s1, 1
	v_lshrrev_b32_e32 v0, 2, v218
	s_and_b32 s10, s4, 0x110
	v_lshrrev_b32_e32 v1, 1, v218
	v_and_b32_e32 v0, 12, v0
	s_movk_i32 s4, 0x1c0
	s_lshr_b32 s3, s2, 3
	v_and_or_b32 v1, v1, s4, v0
	v_and_b32_e32 v127, 0x4f, v218
	v_lshlrev_b32_e32 v124, 9, v1
	v_or_b32_e32 v125, 16, v127
	s_cmp_ge_u32 s3, s10
	v_or_b32_e32 v126, 48, v127
	s_cbranch_scc1 .LBB0_1046
	v_mov_b32_e32 v2, 0x10000
	v_or_b32_e32 v138, 32, v127
	v_lshl_or_b32 v129, v1, 2, v2
	v_bitop3_b32 v2, v0, v127, 1 bitop3:0x36
	v_bitop3_b32 v9, v0, v125, 1 bitop3:0x36
	v_bitop3_b32 v13, v0, v138, 1 bitop3:0x36
	v_bitop3_b32 v17, v0, v126, 1 bitop3:0x36
	v_add_u32_e32 v3, 0x200, v124
	v_lshlrev_b32_e32 v2, 2, v2
	v_lshlrev_b32_e32 v9, 2, v9
	v_lshlrev_b32_e32 v13, 2, v13
	v_lshlrev_b32_e32 v17, 2, v17
	v_or_b32_e32 v131, v3, v2
	s_waitcnt vmcnt(25)
	v_bitop3_b32 v4, v0, v127, 2 bitop3:0x36
	v_or_b32_e32 v135, v3, v9
	v_bitop3_b32 v10, v0, v125, 2 bitop3:0x36
	v_or_b32_e32 v140, v3, v13
	s_waitcnt lgkmcnt(0)
	v_bitop3_b32 v14, v0, v138, 2 bitop3:0x36
	v_or_b32_e32 v144, v3, v17
	v_bitop3_b32 v3, v0, v126, 2 bitop3:0x36
	v_add_u32_e32 v5, 0x400, v124
	v_lshlrev_b32_e32 v4, 2, v4
	v_lshlrev_b32_e32 v10, 2, v10
	v_lshlrev_b32_e32 v14, 2, v14
	v_lshlrev_b32_e32 v3, 2, v3
	v_or_b32_e32 v132, v5, v4
	v_bitop3_b32 v6, v0, v127, 3 bitop3:0x36
	v_or_b32_e32 v136, v5, v10
	v_bitop3_b32 v11, v0, v125, 3 bitop3:0x36
	v_or_b32_e32 v141, v5, v14
	v_bitop3_b32 v15, v0, v138, 3 bitop3:0x36
	v_or_b32_e32 v145, v5, v3
	v_bitop3_b32 v5, v0, v126, 3 bitop3:0x36
	v_add_u32_e32 v7, 0x600, v124
	v_lshlrev_b32_e32 v6, 2, v6
	v_lshlrev_b32_e32 v11, 2, v11
	v_lshlrev_b32_e32 v15, 2, v15
	v_lshlrev_b32_e32 v5, 2, v5
	v_or_b32_e32 v133, v7, v6
	v_or_b32_e32 v137, v7, v11
	v_or_b32_e32 v142, v7, v15
	v_or_b32_e32 v146, v7, v5
	v_bitop3_b32 v7, v0, v127, 16 bitop3:0x36
	v_bitop3_b32 v25, v0, v125, 16 bitop3:0x36
	v_bitop3_b32 v29, v0, v138, 16 bitop3:0x36
	v_bitop3_b32 v33, v0, v126, 16 bitop3:0x36
	v_add_u32_e32 v18, 0x2000, v124
	v_lshlrev_b32_e32 v7, 2, v7
	v_lshlrev_b32_e32 v25, 2, v25
	v_lshlrev_b32_e32 v29, 2, v29
	v_lshlrev_b32_e32 v33, 2, v33
	v_or_b32_e32 v147, v18, v7
	v_bitop3_b32 v19, v0, v127, 17 bitop3:0x36
	v_or_b32_e32 v151, v18, v25
	v_bitop3_b32 v26, v0, v125, 17 bitop3:0x36
	v_or_b32_e32 v155, v18, v29
	v_bitop3_b32 v30, v0, v138, 17 bitop3:0x36
	v_or_b32_e32 v159, v18, v33
	v_bitop3_b32 v18, v0, v126, 17 bitop3:0x36
	v_add_u32_e32 v20, 0x2200, v124
	v_lshlrev_b32_e32 v19, 2, v19
	v_lshlrev_b32_e32 v26, 2, v26
	v_lshlrev_b32_e32 v30, 2, v30
	v_lshlrev_b32_e32 v18, 2, v18
	v_or_b32_e32 v148, v20, v19
	v_bitop3_b32 v21, v0, v127, 18 bitop3:0x36
	v_or_b32_e32 v152, v20, v26
	v_bitop3_b32 v27, v0, v125, 18 bitop3:0x36
	v_or_b32_e32 v156, v20, v30
	v_bitop3_b32 v31, v0, v138, 18 bitop3:0x36
	v_or_b32_e32 v160, v20, v18
	v_bitop3_b32 v20, v0, v126, 18 bitop3:0x36
	v_xor_b32_e32 v1, v0, v127
	v_add_u32_e32 v22, 0x2400, v124
	v_lshlrev_b32_e32 v21, 2, v21
	v_lshlrev_b32_e32 v27, 2, v27
	v_lshlrev_b32_e32 v31, 2, v31
	v_lshlrev_b32_e32 v20, 2, v20
	v_lshlrev_b32_e32 v1, 2, v1
	v_or_b32_e32 v149, v22, v21
	v_or_b32_e32 v153, v22, v27
	v_or_b32_e32 v157, v22, v31
	v_or_b32_e32 v161, v22, v20
	v_add_u32_e32 v22, 0x4000, v124
	v_add_u32_e32 v130, v124, v1
	s_waitcnt vmcnt(18)
	v_or_b32_e32 v163, v22, v1
	v_add_u32_e32 v1, 0x4200, v124
	s_and_b32 s12, s1, 0x88
	v_or_b32_e32 v164, v1, v2
	v_or_b32_e32 v168, v1, v9
	v_or_b32_e32 v172, v1, v13
	v_or_b32_e32 v176, v1, v17
	v_add_u32_e32 v1, 0x6000, v124
	v_or_b32_e32 v179, v1, v7
	v_or_b32_e32 v183, v1, v25
	v_or_b32_e32 v187, v1, v29
	v_or_b32_e32 v191, v1, v33
	v_cvt_f32_ubyte0_e32 v1, s12
	v_rcp_iflag_f32_e32 v1, v1
	v_add_u32_e32 v2, 0x4400, v124
	v_xor_b32_e32 v8, v0, v125
	v_bitop3_b32 v12, v0, v127, 32 bitop3:0x1e
	v_xor_b32_e32 v16, v0, v126
	v_bitop3_b32 v23, v0, v127, 19 bitop3:0x36
	v_bitop3_b32 v28, v0, v125, 19 bitop3:0x36
	v_bitop3_b32 v32, v0, v138, 19 bitop3:0x36
	v_bitop3_b32 v0, v0, v126, 19 bitop3:0x36
	v_or_b32_e32 v165, v2, v4
	v_add_u32_e32 v4, 0x4600, v124
	v_add_u32_e32 v24, 0x2600, v124
	v_lshlrev_b32_e32 v0, 2, v0
	s_waitcnt vmcnt(6)
	v_or_b32_e32 v166, v4, v6
	v_or_b32_e32 v170, v4, v11
	v_or_b32_e32 v174, v4, v15
	v_or_b32_e32 v178, v4, v5
	v_add_u32_e32 v4, 0x6600, v124
	v_or_b32_e32 v162, v24, v0
	v_or_b32_e32 v194, v4, v0
	v_mul_f32_e32 v0, 0x4f7ffffe, v1
	v_cvt_u32_f32_e32 v0, v0
	s_lshl_b32 s15, s0, 7
	s_sub_i32 s0, 0, s12
	v_readlane_b32 s16, v243, 0
	v_readfirstlane_b32 s1, v0
	s_mul_i32 s0, s0, s1
	s_movk_i32 s13, 0x80
	v_lshlrev_b32_e32 v96, 2, v218
	v_lshlrev_b32_e32 v8, 2, v8
	v_lshlrev_b32_e32 v12, 2, v12
	v_lshlrev_b32_e32 v16, 2, v16
	v_lshlrev_b32_e32 v23, 2, v23
	v_lshlrev_b32_e32 v28, 2, v28
	v_lshlrev_b32_e32 v32, 2, v32
	v_or_b32_e32 v169, v2, v10
	v_or_b32_e32 v173, v2, v14
	v_or_b32_e32 v177, v2, v3
	v_add_u32_e32 v2, 0x6200, v124
	v_add_u32_e32 v3, 0x6400, v124
	v_mov_b32_e32 v97, 0
	v_readlane_b32 s17, v243, 1
	v_readlane_b32 s18, v243, 2
	v_readlane_b32 s19, v243, 3
	v_readlane_b32 s20, v243, 4
	v_readlane_b32 s21, v243, 5
	s_mul_hi_u32 s0, s1, s0
	s_lshr_b32 s11, s94, 3
	v_cmp_gt_u32_e64 s[4:5], s13, v218
	v_or_b32_e32 v128, 0x10000, v96
	v_add_u32_e32 v134, v124, v8
	v_add_u32_e32 v139, v124, v12
	v_add_u32_e32 v143, v124, v16
	v_or_b32_e32 v150, v24, v23
	v_or_b32_e32 v154, v24, v28
	v_or_b32_e32 v158, v24, v32
	v_or_b32_e32 v167, v22, v8
	v_or_b32_e32 v171, v22, v12
	v_or_b32_e32 v175, v22, v16
	v_or_b32_e32 v180, v2, v19
	v_or_b32_e32 v181, v3, v21
	v_or_b32_e32 v182, v4, v23
	v_or_b32_e32 v184, v2, v26
	v_or_b32_e32 v185, v3, v27
	v_or_b32_e32 v186, v4, v28
	v_or_b32_e32 v188, v2, v30
	v_or_b32_e32 v189, v3, v31
	v_or_b32_e32 v190, v4, v32
	v_or_b32_e32 v192, v2, v18
	v_or_b32_e32 v193, v3, v20
	s_mov_b32 s14, 0
	v_lshl_add_u64 v[98:99], s[20:21], 0, v[96:97]
	s_add_i32 s16, s1, s0
	v_mov_b32_e32 v195, 0x358637bd
	s_mov_b32 s17, 0x800000
	s_mov_b32 s18, 0x7ffffc0
	s_movk_i32 s19, 0xa0
	s_mov_b64 s[0:1], 0x80
	s_movk_i32 s20, 0xff80
	s_movk_i32 s21, 0xfe44
	s_mov_b32 s6, s3
	v_readlane_b32 s22, v243, 6
	v_readlane_b32 s23, v243, 7
	v_readlane_b32 s24, v243, 8
	v_readlane_b32 s25, v243, 9
	v_readlane_b32 s26, v243, 10
	v_readlane_b32 s27, v243, 11
	v_readlane_b32 s28, v243, 12
	v_readlane_b32 s29, v243, 13
	v_readlane_b32 s30, v243, 14
	v_readlane_b32 s31, v243, 15
	s_branch .LBB0_1034

.LBB0_1037:
	ds_read_b128 v[196:199], v101
	ds_read_b128 v[200:203], v101 offset:2560
	ds_read_b128 v[204:207], v101 offset:5120
	ds_read_b128 v[208:211], v101 offset:7680
	ds_read_b128 v[220:223], v103 offset:20480
	ds_read_b128 v[224:227], v103 offset:23040
	ds_read_b128 v[228:231], v103 offset:25600
	ds_read_b128 v[232:235], v103 offset:28160
	s_add_i32 s7, s7, 64
	s_setprio 1
	s_waitcnt lgkmcnt(3)
	v_mfma_f32_16x16x32_bf16 v[92:95], v[196:199], v[220:223], v[92:95]
	s_waitcnt lgkmcnt(2)
	v_mfma_f32_16x16x32_bf16 v[88:91], v[196:199], v[224:227], v[88:91]
	s_waitcnt lgkmcnt(1)
	v_mfma_f32_16x16x32_bf16 v[80:83], v[196:199], v[228:231], v[80:83]
	s_waitcnt lgkmcnt(0)
	v_mfma_f32_16x16x32_bf16 v[72:75], v[196:199], v[232:235], v[72:75]
	v_mfma_f32_16x16x32_bf16 v[68:71], v[200:203], v[220:223], v[68:71]
	v_mfma_f32_16x16x32_bf16 v[60:63], v[200:203], v[224:227], v[60:63]
	v_mfma_f32_16x16x32_bf16 v[52:55], v[200:203], v[228:231], v[52:55]
	v_mfma_f32_16x16x32_bf16 v[44:47], v[200:203], v[232:235], v[44:47]
	v_mfma_f32_16x16x32_bf16 v[28:31], v[204:207], v[220:223], v[28:31]
	v_mfma_f32_16x16x32_bf16 v[24:27], v[204:207], v[224:227], v[24:27]
	v_mfma_f32_16x16x32_bf16 v[20:23], v[204:207], v[228:231], v[20:23]
	v_mfma_f32_16x16x32_bf16 v[16:19], v[204:207], v[232:235], v[16:19]
	v_mfma_f32_16x16x32_bf16 v[12:15], v[208:211], v[220:223], v[12:15]
	v_mfma_f32_16x16x32_bf16 v[8:11], v[208:211], v[224:227], v[8:11]
	v_mfma_f32_16x16x32_bf16 v[4:7], v[208:211], v[228:231], v[4:7]
	v_mfma_f32_16x16x32_bf16 v[0:3], v[208:211], v[232:235], v[0:3]
	s_cmp_lg_u32 s34, 0
	s_cbranch_scc1 .Lfv_4
	s_setprio 0
.Lfv_4:
	ds_read_b128 v[196:199], v101 offset:64
	ds_read_b128 v[200:203], v101 offset:2624
	ds_read_b128 v[204:207], v101 offset:5184
	ds_read_b128 v[208:211], v101 offset:7744
	ds_read_b128 v[220:223], v103 offset:20544
	ds_read_b128 v[224:227], v103 offset:23104
	ds_read_b128 v[228:231], v103 offset:25664
	ds_read_b128 v[232:235], v103 offset:28224
	s_setprio 1
	s_waitcnt lgkmcnt(3)
	v_mfma_f32_16x16x32_bf16 v[92:95], v[196:199], v[220:223], v[92:95]
	s_waitcnt lgkmcnt(2)
	v_mfma_f32_16x16x32_bf16 v[88:91], v[196:199], v[224:227], v[88:91]
	s_waitcnt lgkmcnt(1)
	v_mfma_f32_16x16x32_bf16 v[80:83], v[196:199], v[228:231], v[80:83]
	s_waitcnt lgkmcnt(0)
	v_mfma_f32_16x16x32_bf16 v[72:75], v[196:199], v[232:235], v[72:75]
	v_mfma_f32_16x16x32_bf16 v[68:71], v[200:203], v[220:223], v[68:71]
	v_mfma_f32_16x16x32_bf16 v[60:63], v[200:203], v[224:227], v[60:63]
	v_mfma_f32_16x16x32_bf16 v[52:55], v[200:203], v[228:231], v[52:55]
	v_mfma_f32_16x16x32_bf16 v[44:47], v[200:203], v[232:235], v[44:47]
	v_mfma_f32_16x16x32_bf16 v[28:31], v[204:207], v[220:223], v[28:31]
	v_mfma_f32_16x16x32_bf16 v[24:27], v[204:207], v[224:227], v[24:27]
	v_mfma_f32_16x16x32_bf16 v[20:23], v[204:207], v[228:231], v[20:23]
	v_mfma_f32_16x16x32_bf16 v[16:19], v[204:207], v[232:235], v[16:19]
	v_mfma_f32_16x16x32_bf16 v[12:15], v[208:211], v[220:223], v[12:15]
	v_mfma_f32_16x16x32_bf16 v[8:11], v[208:211], v[224:227], v[8:11]
	v_mfma_f32_16x16x32_bf16 v[4:7], v[208:211], v[228:231], v[4:7]
	v_mfma_f32_16x16x32_bf16 v[0:3], v[208:211], v[232:235], v[0:3]
	s_cmp_lg_u32 s34, 0
	s_cbranch_scc1 .Lfv_5
	s_setprio 0
.Lfv_5:
	v_lshl_add_u64 v[108:109], v[108:109], 0, s[0:1]
	v_lshl_add_u64 v[110:111], v[110:111], 0, s[0:1]
	v_lshl_add_u64 v[112:113], v[112:113], 0, s[0:1]
	v_lshl_add_u64 v[114:115], v[114:115], 0, s[0:1]
	v_lshl_add_u64 v[116:117], v[116:117], 0, s[0:1]
	v_lshl_add_u64 v[118:119], v[118:119], 0, s[0:1]
	v_lshl_add_u64 v[120:121], v[120:121], 0, s[0:1]
	s_andn2_b64 vcc, exec, s[8:9]
	v_lshl_add_u64 v[122:123], v[122:123], 0, s[0:1]
	s_cbranch_vccz .LBB0_1040

.LBB0_1051:
	ds_read_b128 v[162:165], v128
	ds_read_b128 v[166:169], v128 offset:2560
	ds_read_b128 v[170:173], v128 offset:5120
	ds_read_b128 v[174:177], v128 offset:7680
	ds_read_b128 v[178:181], v147 offset:20480
	ds_read_b128 v[182:185], v147 offset:23040
	ds_read_b128 v[186:189], v147 offset:25600
	ds_read_b128 v[190:193], v147 offset:28160
	s_setprio 1
	s_waitcnt lgkmcnt(3)
	v_mfma_f32_16x16x32_bf16 v[64:67], v[162:165], v[178:181], v[64:67]
	s_waitcnt lgkmcnt(2)
	v_mfma_f32_16x16x32_bf16 v[68:71], v[162:165], v[182:185], v[68:71]
	s_waitcnt lgkmcnt(1)
	v_mfma_f32_16x16x32_bf16 v[72:75], v[162:165], v[186:189], v[72:75]
	s_waitcnt lgkmcnt(0)
	v_mfma_f32_16x16x32_bf16 v[76:79], v[162:165], v[190:193], v[76:79]
	v_mfma_f32_16x16x32_bf16 v[80:83], v[166:169], v[178:181], v[80:83]
	v_mfma_f32_16x16x32_bf16 v[84:87], v[166:169], v[182:185], v[84:87]
	v_mfma_f32_16x16x32_bf16 v[88:91], v[166:169], v[186:189], v[88:91]
	v_mfma_f32_16x16x32_bf16 v[92:95], v[166:169], v[190:193], v[92:95]
	v_mfma_f32_16x16x32_bf16 v[162:165], v[170:173], v[178:181], v[96:99]
	v_mfma_f32_16x16x32_bf16 v[166:169], v[170:173], v[182:185], v[100:103]
	v_mfma_f32_16x16x32_bf16 v[194:197], v[170:173], v[186:189], v[104:107]
	v_mfma_f32_16x16x32_bf16 v[170:173], v[170:173], v[190:193], v[108:111]
	v_mfma_f32_16x16x32_bf16 v[178:181], v[174:177], v[178:181], v[112:115]
	v_mfma_f32_16x16x32_bf16 v[182:185], v[174:177], v[182:185], v[116:119]
	v_mfma_f32_16x16x32_bf16 v[186:189], v[174:177], v[186:189], v[120:123]
	v_mfma_f32_16x16x32_bf16 v[174:177], v[174:177], v[190:193], v[124:127]
	s_cmp_lg_u32 s34, 0
	s_cbranch_scc1 .Lfv_6
	s_setprio 0
.Lfv_6:
	ds_read_b128 v[96:99], v128 offset:64
	ds_read_b128 v[190:193], v128 offset:2624
	ds_read_b128 v[198:201], v128 offset:5184
	ds_read_b128 v[202:205], v128 offset:7744
	ds_read_b128 v[206:209], v147 offset:20544
	ds_read_b128 v[210:213], v147 offset:23104
	ds_read_b128 v[220:223], v147 offset:25664
	ds_read_b128 v[224:227], v147 offset:28224
	s_setprio 1
	s_waitcnt lgkmcnt(3)
	v_mfma_f32_16x16x32_bf16 v[124:127], v[96:99], v[206:209], v[64:67]
	s_waitcnt lgkmcnt(2)
	v_mfma_f32_16x16x32_bf16 v[120:123], v[96:99], v[210:213], v[68:71]
	s_waitcnt lgkmcnt(1)
	v_mfma_f32_16x16x32_bf16 v[116:119], v[96:99], v[220:223], v[72:75]
	s_waitcnt lgkmcnt(0)
	v_mfma_f32_16x16x32_bf16 v[112:115], v[96:99], v[224:227], v[76:79]
	v_mfma_f32_16x16x32_bf16 v[108:111], v[190:193], v[206:209], v[80:83]
	v_mfma_f32_16x16x32_bf16 v[104:107], v[190:193], v[210:213], v[84:87]
	v_mfma_f32_16x16x32_bf16 v[100:103], v[190:193], v[220:223], v[88:91]
	v_mfma_f32_16x16x32_bf16 v[96:99], v[190:193], v[224:227], v[92:95]
	v_mfma_f32_16x16x32_bf16 v[92:95], v[198:201], v[206:209], v[162:165]
	v_mfma_f32_16x16x32_bf16 v[88:91], v[198:201], v[210:213], v[166:169]
	v_mfma_f32_16x16x32_bf16 v[84:87], v[198:201], v[220:223], v[194:197]
	v_mfma_f32_16x16x32_bf16 v[80:83], v[198:201], v[224:227], v[170:173]
	v_mfma_f32_16x16x32_bf16 v[76:79], v[202:205], v[206:209], v[178:181]
	v_mfma_f32_16x16x32_bf16 v[72:75], v[202:205], v[210:213], v[182:185]
	v_mfma_f32_16x16x32_bf16 v[68:71], v[202:205], v[220:223], v[186:189]
	v_mfma_f32_16x16x32_bf16 v[64:67], v[202:205], v[224:227], v[174:177]
	s_cmp_lg_u32 s34, 0
	s_cbranch_scc1 .Lfv_7
	s_setprio 0
.Lfv_7:
	s_andn2_b64 vcc, exec, s[4:5]
	s_mov_b64 s[0:1], 0
	s_cbranch_vccz .LBB0_1056

.LBB0_1054:
	ds_read_b128 v[162:165], v128
	ds_read_b128 v[166:169], v128 offset:2560
	ds_read_b128 v[170:173], v128 offset:5120
	ds_read_b128 v[174:177], v128 offset:7680
	ds_read_b128 v[178:181], v147 offset:20480
	ds_read_b128 v[182:185], v147 offset:23040
	ds_read_b128 v[186:189], v147 offset:25600
	ds_read_b128 v[190:193], v147 offset:28160
	s_setprio 1
	s_waitcnt lgkmcnt(3)
	v_mfma_f32_16x16x32_bf16 v[124:127], v[162:165], v[178:181], v[124:127]
	s_waitcnt lgkmcnt(2)
	v_mfma_f32_16x16x32_bf16 v[120:123], v[162:165], v[182:185], v[120:123]
	s_waitcnt lgkmcnt(1)
	v_mfma_f32_16x16x32_bf16 v[116:119], v[162:165], v[186:189], v[116:119]
	s_waitcnt lgkmcnt(0)
	v_mfma_f32_16x16x32_bf16 v[112:115], v[162:165], v[190:193], v[112:115]
	v_mfma_f32_16x16x32_bf16 v[108:111], v[166:169], v[178:181], v[108:111]
	v_mfma_f32_16x16x32_bf16 v[104:107], v[166:169], v[182:185], v[104:107]
	v_mfma_f32_16x16x32_bf16 v[100:103], v[166:169], v[186:189], v[100:103]
	v_mfma_f32_16x16x32_bf16 v[96:99], v[166:169], v[190:193], v[96:99]
	v_mfma_f32_16x16x32_bf16 v[162:165], v[170:173], v[178:181], v[92:95]
	v_mfma_f32_16x16x32_bf16 v[166:169], v[170:173], v[182:185], v[88:91]
	v_mfma_f32_16x16x32_bf16 v[194:197], v[170:173], v[186:189], v[84:87]
	v_mfma_f32_16x16x32_bf16 v[170:173], v[170:173], v[190:193], v[80:83]
	v_mfma_f32_16x16x32_bf16 v[178:181], v[174:177], v[178:181], v[76:79]
	v_mfma_f32_16x16x32_bf16 v[182:185], v[174:177], v[182:185], v[72:75]
	v_mfma_f32_16x16x32_bf16 v[186:189], v[174:177], v[186:189], v[68:71]
	v_mfma_f32_16x16x32_bf16 v[174:177], v[174:177], v[190:193], v[64:67]
	s_cmp_lg_u32 s34, 0
	s_cbranch_scc1 .Lfv_8
	s_setprio 0
.Lfv_8:
	ds_read_b128 v[76:79], v128 offset:64
	ds_read_b128 v[92:95], v128 offset:2624
	ds_read_b128 v[190:193], v128 offset:5184
	ds_read_b128 v[198:201], v128 offset:7744
	ds_read_b128 v[202:205], v147 offset:20544
	ds_read_b128 v[206:209], v147 offset:23104
	ds_read_b128 v[210:213], v147 offset:25664
	ds_read_b128 v[220:223], v147 offset:28224
	s_setprio 1
	s_waitcnt lgkmcnt(3)
	v_mfma_f32_16x16x32_bf16 v[64:67], v[76:79], v[202:205], v[124:127]
	s_waitcnt lgkmcnt(2)
	v_mfma_f32_16x16x32_bf16 v[68:71], v[76:79], v[206:209], v[120:123]
	s_waitcnt lgkmcnt(1)
	v_mfma_f32_16x16x32_bf16 v[72:75], v[76:79], v[210:213], v[116:119]
	s_waitcnt lgkmcnt(0)
	v_mfma_f32_16x16x32_bf16 v[76:79], v[76:79], v[220:223], v[112:115]
	v_mfma_f32_16x16x32_bf16 v[80:83], v[92:95], v[202:205], v[108:111]
	v_mfma_f32_16x16x32_bf16 v[84:87], v[92:95], v[206:209], v[104:107]
	v_mfma_f32_16x16x32_bf16 v[88:91], v[92:95], v[210:213], v[100:103]
	v_mfma_f32_16x16x32_bf16 v[92:95], v[92:95], v[220:223], v[96:99]
	v_mfma_f32_16x16x32_bf16 v[96:99], v[190:193], v[202:205], v[162:165]
	v_mfma_f32_16x16x32_bf16 v[100:103], v[190:193], v[206:209], v[166:169]
	v_mfma_f32_16x16x32_bf16 v[104:107], v[190:193], v[210:213], v[194:197]
	v_mfma_f32_16x16x32_bf16 v[108:111], v[190:193], v[220:223], v[170:173]
	v_mfma_f32_16x16x32_bf16 v[112:115], v[198:201], v[202:205], v[178:181]
	v_mfma_f32_16x16x32_bf16 v[116:119], v[198:201], v[206:209], v[182:185]
	v_mfma_f32_16x16x32_bf16 v[120:123], v[198:201], v[210:213], v[186:189]
	v_mfma_f32_16x16x32_bf16 v[124:127], v[198:201], v[220:223], v[174:177]
	s_cmp_lg_u32 s34, 0
	s_cbranch_scc1 .Lfv_9
	s_setprio 0
.Lfv_9:
	s_andn2_b64 vcc, exec, s[0:1]
	s_barrier
	ds_write_b128 v146, v[20:23]
	ds_write_b128 v146, v[16:19] offset:20480
	ds_write_b128 v148, v[36:39]
	ds_write_b128 v148, v[28:31] offset:20480
	ds_write_b128 v150, v[48:51]
	ds_write_b128 v150, v[44:47] offset:20480
	ds_write_b128 v152, v[60:63]
	s_waitcnt vmcnt(0)
	ds_write_b128 v152, v[56:59] offset:20480
	s_waitcnt lgkmcnt(0)
	s_barrier
	s_cbranch_vccnz .LBB0_1051
	global_load_dwordx4 v[20:23], v[130:131], off offset:768
	global_load_dwordx4 v[36:39], v[130:131], off offset:784
	global_load_dwordx4 v[48:51], v[132:133], off offset:768
	global_load_dwordx4 v[60:63], v[132:133], off offset:784
	global_load_dwordx4 v[162:165], v[134:135], off offset:768
	global_load_dwordx4 v[166:169], v[134:135], off offset:784
	global_load_dwordx4 v[170:173], v[136:137], off offset:784
	global_load_dwordx4 v[174:177], v[136:137], off offset:768
	global_load_dwordx4 v[16:19], v[138:139], off offset:384
	global_load_dwordx4 v[28:31], v[140:141], off offset:384
	global_load_dwordx4 v[44:47], v[142:143], off offset:384
	global_load_dwordx4 v[56:59], v[144:145], off offset:384
	s_waitcnt vmcnt(11)
	v_cvt_pk_bf16_f32 v20, v20, v21
	v_cvt_pk_bf16_f32 v21, v22, v23
	s_waitcnt vmcnt(10)
	v_cvt_pk_bf16_f32 v22, v36, v37
	v_cvt_pk_bf16_f32 v23, v38, v39
	s_waitcnt vmcnt(9)
	v_cvt_pk_bf16_f32 v36, v48, v49
	v_cvt_pk_bf16_f32 v37, v50, v51
	s_waitcnt vmcnt(8)
	v_cvt_pk_bf16_f32 v38, v60, v61
	v_cvt_pk_bf16_f32 v39, v62, v63
	s_waitcnt vmcnt(7)
	v_cvt_pk_bf16_f32 v48, v162, v163
	v_cvt_pk_bf16_f32 v49, v164, v165
	s_waitcnt vmcnt(6)
	v_cvt_pk_bf16_f32 v50, v166, v167
	v_cvt_pk_bf16_f32 v51, v168, v169
	s_waitcnt vmcnt(4)
	v_cvt_pk_bf16_f32 v60, v174, v175
	v_cvt_pk_bf16_f32 v61, v176, v177
	v_cvt_pk_bf16_f32 v62, v170, v171
	v_cvt_pk_bf16_f32 v63, v172, v173
	s_branch .LBB0_1051

.LBB0_1113:
	s_setprio 0
	s_cmp_lt_i32 s92, 10
	s_cselect_b64 s[0:1], -1, 0
	s_cmp_gt_i32 s93, 9
	s_cselect_b64 s[4:5], -1, 0
	s_and_b64 s[0:1], s[0:1], s[4:5]
	s_andn2_b64 vcc, exec, s[0:1]
	s_cbranch_vccnz .LBB0_1592
	v_lshl_add_u32 v96, s2, 2, v214
	s_movk_i32 s0, 0x4200
	v_cmp_gt_i32_e32 vcc, s0, v96
	s_and_saveexec_b64 s[28:29], vcc
	s_cbranch_execz .LBB0_1538
	s_waitcnt vmcnt(25)
	v_mbcnt_lo_u32_b32 v6, -1, 0
	v_mbcnt_hi_u32_b32 v6, -1, v6
	v_and_b32_e32 v7, 64, v6
	v_add_u32_e32 v7, 64, v7
	v_xor_b32_e32 v8, 32, v6
	v_cmp_lt_i32_e64 s[0:1], v8, v7
	v_and_b32_e32 v4, 63, v218
	v_add_u32_e32 v0, -16, v4
	v_cndmask_b32_e64 v8, v6, v8, s[0:1]
	v_lshlrev_b32_e32 v137, 2, v8
	v_xor_b32_e32 v8, 16, v6
	v_cmp_lt_i32_e64 s[0:1], v8, v7
	v_min_u32_e32 v0, v0, v4
	v_subrev_co_u32_e32 v1, vcc, 24, v4
	v_cndmask_b32_e64 v8, v6, v8, s[0:1]
	v_lshlrev_b32_e32 v138, 2, v8
	v_xor_b32_e32 v8, 8, v6
	v_cmp_lt_i32_e64 s[0:1], v8, v7
	v_cndmask_b32_e32 v0, v1, v0, vcc
	v_subrev_co_u32_e64 v1, s[18:19], 29, v4
	v_cndmask_b32_e64 v8, v6, v8, s[0:1]
	v_lshlrev_b32_e32 v139, 2, v8
	v_xor_b32_e32 v8, 4, v6
	v_cmp_lt_i32_e64 s[0:1], v8, v7
	v_mul_u32_u24_e32 v136, 0x500, v214
	v_cndmask_b32_e64 v0, v1, v0, s[18:19]
	v_cndmask_b32_e64 v8, v6, v8, s[0:1]
	v_lshlrev_b32_e32 v140, 2, v8
	v_xor_b32_e32 v8, 2, v6
	v_cmp_lt_i32_e64 s[0:1], v8, v7
	v_subrev_co_u32_e64 v1, s[20:21], 33, v4
	s_nop 0
	v_cndmask_b32_e64 v8, v6, v8, s[0:1]
	v_lshlrev_b32_e32 v141, 2, v8
	v_xor_b32_e32 v8, 1, v6
	v_cmp_lt_i32_e64 s[0:1], v8, v7
	v_and_b32_e32 v7, 58, v218
	v_cndmask_b32_e64 v0, v1, v0, s[20:21]
	v_cndmask_b32_e64 v6, v6, v8, s[0:1]
	v_cmp_ne_u32_e64 s[0:1], 0, v4
	v_lshlrev_b32_e32 v142, 2, v6
	v_and_b32_e32 v6, 1, v218
	v_cndmask_b32_e64 v144, 0, 1, s[0:1]
	v_cmp_lt_u32_e64 s[0:1], 1, v4
	v_cmp_eq_u32_e64 s[6:7], 0, v6
	v_and_b32_e32 v6, 2, v218
	v_cndmask_b32_e64 v145, 0, 1, s[0:1]
	v_cmp_lt_u32_e64 s[0:1], 2, v4
	v_lshlrev_b32_e32 v8, 4, v218
	v_subrev_co_u32_e64 v1, s[22:23], 36, v4
	v_cndmask_b32_e64 v146, 0, 1, s[0:1]
	v_cmp_lt_u32_e64 s[0:1], 3, v4
	v_cmp_eq_u32_e64 s[8:9], 0, v6
	v_and_b32_e32 v6, 4, v218
	v_cndmask_b32_e64 v147, 0, 1, s[0:1]
	v_cmp_lt_u32_e64 s[0:1], 4, v4
	v_and_or_b32 v8, v8, 16, v136
	v_lshlrev_b32_e32 v7, 2, v7
	v_cndmask_b32_e64 v148, 0, 1, s[0:1]
	v_cmp_lt_u32_e64 s[0:1], 5, v4
	v_cndmask_b32_e64 v0, v1, v0, s[22:23]
	v_subrev_co_u32_e64 v1, s[26:27], 38, v4
	v_cndmask_b32_e64 v149, 0, 1, s[0:1]
	v_cmp_lt_u32_e64 s[0:1], 6, v4
	v_cmp_eq_u32_e64 s[10:11], 0, v6
	v_or3_b32 v195, v8, v7, v6
	v_cndmask_b32_e64 v150, 0, 1, s[0:1]
	v_cmp_lt_u32_e64 s[0:1], 7, v4
	v_cndmask_b32_e64 v2, v1, v0, s[26:27]
	v_subrev_co_u32_e64 v3, s[24:25], 40, v4
	v_cndmask_b32_e64 v151, 0, 1, s[0:1]
	v_cmp_lt_u32_e64 s[0:1], 8, v4
	v_subrev_u32_e32 v0, 34, v4
	v_cmp_gt_u32_e64 s[4:5], 50, v4
	v_cndmask_b32_e64 v152, 0, 1, s[0:1]
	v_cmp_lt_u32_e64 s[0:1], 9, v4
	v_readlane_b32 s36, v242, 25
	v_cndmask_b32_e64 v5, 0, v0, s[4:5]
	v_cndmask_b32_e64 v153, 0, 1, s[0:1]
	v_cmp_lt_u32_e64 s[0:1], 10, v4
	v_lshlrev_b32_e32 v0, 4, v4
	v_mov_b32_e32 v1, 0
	v_cndmask_b32_e64 v154, 0, 1, s[0:1]
	v_cmp_lt_u32_e64 s[0:1], 11, v4
	v_readlane_b32 s38, v242, 27
	v_readlane_b32 s39, v242, 28
	v_cndmask_b32_e64 v155, 0, 1, s[0:1]
	v_cmp_lt_u32_e64 s[0:1], 12, v4
	v_lshl_add_u64 v[106:107], s[38:39], 0, v[0:1]
	v_lshlrev_b32_e32 v0, 5, v4
	v_cndmask_b32_e64 v156, 0, 1, s[0:1]
	v_cmp_lt_u32_e64 s[0:1], 13, v4
	v_mov_b32_e32 v101, v1
	v_mov_b32_e32 v99, v1
	v_cndmask_b32_e64 v157, 0, 1, s[0:1]
	v_cmp_lt_u32_e64 s[0:1], 14, v4
	v_lshl_add_u64 v[110:111], s[82:83], 0, v[0:1]
	v_readlane_b32 s64, v242, 1
	v_cndmask_b32_e64 v158, 0, 1, s[0:1]
	v_cmp_lt_u32_e64 s[0:1], 15, v4
	v_readlane_b32 s65, v242, 2
	v_readlane_b32 s66, v242, 3
	v_cndmask_b32_e64 v159, 0, 1, s[0:1]
	v_cmp_lt_u32_e64 s[0:1], 16, v4
	v_cndmask_b32_e32 v6, 2, v159, vcc
	v_cndmask_b32_e64 v6, 3, v6, s[18:19]
	v_cndmask_b32_e64 v160, 0, 1, s[0:1]
	v_cmp_lt_u32_e64 s[0:1], 17, v4
	v_cmp_gt_u32_e32 vcc, 42, v4
	v_cndmask_b32_e64 v6, 4, v6, s[20:21]
	v_cndmask_b32_e64 v161, 0, 1, s[0:1]
	v_cmp_lt_u32_e64 s[0:1], 18, v4
	v_cndmask_b32_e32 v3, 0, v3, vcc
	v_cndmask_b32_e64 v6, 5, v6, s[22:23]
	s_waitcnt vmcnt(18)
	v_cndmask_b32_e64 v162, 0, 1, s[0:1]
	v_cmp_lt_u32_e64 s[0:1], 19, v4
	v_cndmask_b32_e64 v98, v3, v2, s[24:25]
	v_cndmask_b32_e64 v6, 6, v6, s[26:27]
	v_cndmask_b32_e64 v163, 0, 1, s[0:1]
	v_cmp_lt_u32_e64 s[0:1], 20, v4
	v_cndmask_b32_e64 v5, v5, 7, vcc
	v_mov_b32_e32 v3, v1
	v_cndmask_b32_e64 v164, 0, 1, s[0:1]
	v_cmp_lt_u32_e64 s[0:1], 21, v4
	v_ashrrev_i32_e32 v1, 31, v98
	v_mov_b32_e32 v0, v98
	v_cndmask_b32_e64 v165, 0, 1, s[0:1]
	v_cmp_lt_u32_e64 s[0:1], 22, v4
	v_cndmask_b32_e64 v100, v5, v6, s[24:25]
	v_lshl_add_u64 v[0:1], v[0:1], 2, s[84:85]
	s_waitcnt vmcnt(6)
	v_cndmask_b32_e64 v166, 0, 1, s[0:1]
	v_cmp_lt_u32_e64 s[0:1], 23, v4
	v_lshlrev_b32_e32 v2, 6, v4
	v_readlane_b32 s67, v242, 4
	v_cndmask_b32_e64 v167, 0, 1, s[0:1]
	v_cmp_lt_u32_e64 s[0:1], 24, v4
	v_readlane_b32 s68, v242, 5
	v_readlane_b32 s69, v242, 6
	v_cndmask_b32_e64 v168, 0, 1, s[0:1]
	v_cmp_lt_u32_e64 s[0:1], 25, v4
	v_readlane_b32 s70, v242, 7
	v_readlane_b32 s71, v242, 8
	v_cndmask_b32_e64 v169, 0, 1, s[0:1]
	v_cmp_lt_u32_e64 s[0:1], 26, v4
	v_readlane_b32 s72, v242, 9
	v_readlane_b32 s73, v242, 10
	v_cndmask_b32_e64 v170, 0, 1, s[0:1]
	v_cmp_lt_u32_e64 s[0:1], 27, v4
	v_readlane_b32 s74, v242, 11
	v_readlane_b32 s75, v242, 12
	v_cndmask_b32_e64 v171, 0, 1, s[0:1]
	v_cmp_lt_u32_e64 s[0:1], 28, v4
	v_readlane_b32 s76, v242, 13
	v_readlane_b32 s77, v242, 14
	v_cndmask_b32_e64 v172, 0, 1, s[0:1]
	v_cmp_lt_u32_e64 s[0:1], 29, v4
	v_readlane_b32 s78, v242, 15
	v_readlane_b32 s79, v242, 16
	v_cndmask_b32_e64 v173, 0, 1, s[0:1]
	v_cmp_lt_u32_e64 s[0:1], 30, v4
	v_lshl_add_u64 v[102:103], s[64:65], 0, v[2:3]
	v_readlane_b32 s64, v243, 33
	v_cndmask_b32_e64 v174, 0, 1, s[0:1]
	v_cmp_lt_u32_e64 s[0:1], 31, v4
	s_movk_i32 s30, 0x500
	v_bfe_u32 v194, v218, 3, 3
	v_cndmask_b32_e64 v175, 0, 1, s[0:1]
	v_cmp_lt_u32_e64 s[0:1], 32, v4
	v_readlane_b32 s42, v242, 31
	v_readlane_b32 s65, v243, 34
	v_cndmask_b32_e64 v176, 0, 1, s[0:1]
	v_cmp_lt_u32_e64 s[0:1], 33, v4
	v_readlane_b32 s66, v243, 35
	v_readlane_b32 s67, v243, 36
	v_cndmask_b32_e64 v177, 0, 1, s[0:1]
	v_cmp_lt_u32_e64 s[0:1], 34, v4
	v_readlane_b32 s68, v243, 37
	v_readlane_b32 s78, v243, 47
	v_cndmask_b32_e64 v178, 0, 1, s[0:1]
	v_cmp_lt_u32_e64 s[0:1], 35, v4
	v_readlane_b32 s79, v243, 48
	v_lshl_or_b32 v143, v4, 2, v136
	v_cndmask_b32_e64 v179, 0, 1, s[0:1]
	v_cmp_lt_u32_e64 s[0:1], 36, v4
	v_cmp_eq_u32_e64 s[12:13], 6, v194
	v_cmp_eq_u32_e64 s[14:15], 7, v194
	v_cndmask_b32_e64 v180, 0, 1, s[0:1]
	v_cmp_lt_u32_e64 s[0:1], 37, v4
	v_cmp_eq_u32_e64 s[16:17], 0, v4
	s_lshl_b32 s3, s42, 2
	v_cndmask_b32_e64 v181, 0, 1, s[0:1]
	v_cmp_lt_u32_e64 s[0:1], 38, v4
	v_lshl_add_u64 v[104:105], s[78:79], 0, v[2:3]
	s_mov_b64 s[18:19], 0
	v_cndmask_b32_e64 v182, 0, 1, s[0:1]
	v_cmp_lt_u32_e64 s[0:1], 39, v4
	v_mov_b32_e32 v197, 0xff61b1e6
	s_movk_i32 s31, 0x3f80
	v_cndmask_b32_e64 v183, 0, 1, s[0:1]
	v_cmp_lt_u32_e64 s[0:1], 40, v4
	s_mov_b64 s[20:21], 0x80
	s_waitcnt vmcnt(4)
	v_mov_b32_e32 v198, 0x358637bd
	v_cndmask_b32_e64 v184, 0, 1, s[0:1]
	v_cmp_lt_u32_e64 s[0:1], 41, v4
	s_mov_b32 s35, 0x800000
	s_mov_b32 s54, 0x378e98ab
	v_cndmask_b32_e64 v185, 0, 1, s[0:1]
	v_cmp_lt_u32_e64 s[0:1], 42, v4
	s_mov_b32 s55, 0x3b7cd369
	s_mov_b32 s56, 0xbcc618b2
	v_cndmask_b32_e64 v186, 0, 1, s[0:1]
	v_cmp_lt_u32_e64 s[0:1], 43, v4
	s_mov_b32 s57, 0x3dda74e4
	s_mov_b32 s62, 0x3f228afd
	v_cndmask_b32_e64 v187, 0, 1, s[0:1]
	v_cmp_lt_u32_e64 s[0:1], 44, v4
	s_mov_b32 s63, 0x3e03c728
	s_mov_b32 s64, 0xbfb8aa3b
	v_cndmask_b32_e64 v188, 0, 1, s[0:1]
	v_cmp_lt_u32_e64 s[0:1], 45, v4
	s_mov_b32 s65, 0x42ce8ed0
	s_mov_b32 s66, 0xc2b17218
	v_cndmask_b32_e64 v189, 0, 1, s[0:1]
	v_cmp_lt_u32_e64 s[0:1], 46, v4
	v_mov_b32_e32 v199, 0x3ba10414
	s_brev_b32 s67, -2
	v_cndmask_b32_e64 v190, 0, 1, s[0:1]
	v_cmp_lt_u32_e64 s[0:1], 47, v4
	s_movk_i32 s68, 0x41ff
	v_mov_b32_e32 v200, 0xb9c68948
	v_cndmask_b32_e64 v191, 0, 1, s[0:1]
	v_cmp_lt_u32_e64 s[0:1], 48, v4
	v_mov_b32_e32 v201, 0x7f800000
	v_readlane_b32 s37, v242, 26
	v_cndmask_b32_e64 v192, 0, 1, s[0:1]
	v_cmp_lt_u32_e64 s[0:1], 49, v4
	v_readlane_b32 s40, v242, 29
	v_readlane_b32 s41, v242, 30
	v_cndmask_b32_e64 v193, 0, 1, s[0:1]
	s_mov_b64 s[0:1], 0x1000000
	v_lshl_add_u64 v[108:109], v[106:107], 0, s[0:1]
	s_mov_b64 s[0:1], 0xc0
	v_lshl_add_u64 v[112:113], v[0:1], 0, s[0:1]
	v_add_u32_e32 v0, 32, v100
	v_ashrrev_i32_e32 v1, 31, v0
	v_lshl_add_u64 v[114:115], v[0:1], 2, s[84:85]
	v_mov_b32_e32 v0, 0x120
	v_mad_u32_u24 v196, v214, s30, v0
	v_readlane_b32 s43, v242, 32
	v_readlane_b32 s69, v243, 38
	v_readlane_b32 s70, v243, 39
	v_readlane_b32 s71, v243, 40
	v_readlane_b32 s72, v243, 41
	v_readlane_b32 s73, v243, 42
	v_readlane_b32 s74, v243, 43
	v_readlane_b32 s75, v243, 44
	v_readlane_b32 s76, v243, 45
	v_readlane_b32 s77, v243, 46
	s_mov_b32 s26, 0
	v_readfirstlane_b32 s47, v214
	v_and_b32_e32 v202, 63, v218
	v_mul_u32_u24_e32 v204, 0x3640, v214
	v_lshlrev_b32_e32 v202, 2, v202
	v_add_u32_e32 v204, 0x1400, v204
	v_add_u32_e32 v202, v202, v204
	v_add_u32_e32 v204, 0x3600, v204
	v_mov_b32_e32 v203, 0
	s_branch .LBB0_1117

.LBB0_1592:
	s_cmp_lt_i32 s92, 11
	s_cselect_b64 s[0:1], -1, 0
	s_cmp_gt_i32 s93, 10
	s_cselect_b64 s[4:5], -1, 0
	s_and_b64 s[0:1], s[0:1], s[4:5]
	s_andn2_b64 vcc, exec, s[0:1]
	s_cbranch_vccnz .LBB0_1662
	s_and_b32 s34, s2, 4
	s_cmp_eq_u32 s34, 0
	s_cselect_b32 s34, 1, 0
	s_cmp_lt_u32 s2, 64
	s_cselect_b32 s34, s34, 0
	s_and_b32 s3, s2, 7
	s_sub_i32 s0, 0x8b, s3
	s_lshr_b32 s16, s2, 3
	s_and_b32 s17, s0, 0x88
	s_cmp_ge_u32 s16, s17
	s_cbranch_scc1 .LBB0_1608
	v_lshrrev_b32_e32 v1, 2, v218
	v_lshrrev_b32_e32 v0, 1, v218
	v_and_b32_e32 v1, 12, v1
	s_movk_i32 s0, 0x1c0
	v_and_or_b32 v0, v0, s0, v1
	v_and_b32_e32 v1, 0x4f, v218
	v_and_b32_e32 v2, 16, v218
	v_and_b32_e32 v3, 0x5f, v218
	s_waitcnt vmcnt(25)
	v_bitop3_b32 v4, v1, v218, 16 bitop3:0x72
	v_bitop3_b32 v1, v1, v2, 48 bitop3:0x36
	v_lshlrev_b32_e32 v3, 2, v3
	v_lshlrev_b32_e32 v0, 9, v0
	v_lshlrev_b32_e32 v4, 2, v4
	v_lshlrev_b32_e32 v1, 2, v1
	s_waitcnt vmcnt(7)
	v_add_u32_e32 v170, v3, v0
	v_add_u32_e32 v171, v4, v0
	v_add_u32_e32 v172, v1, v0
	v_mbcnt_lo_u32_b32 v0, -1, 0
	s_lshr_b32 s18, s94, 3
	s_lshl_b32 s19, s3, 7
	s_mov_b32 s11, 0
	v_mov_b32_e32 v129, 0
	s_mov_b32 s20, 0x7ffffc0
	s_movk_i32 s21, 0xa0
	s_mov_b64 s[12:13], 0x100
	v_mbcnt_hi_u32_b32 v173, -1, v0
	s_mov_b32 s4, s16
	s_mov_b32 s22, 0
	s_branch .LBB0_1596

.LBB0_1597:
	ds_read_b128 v[154:157], v131
	ds_read_b128 v[158:161], v131 offset:2560
	ds_read_b128 v[162:165], v131 offset:5120
	ds_read_b128 v[166:169], v131 offset:7680
	ds_read_b128 v[174:177], v133 offset:20480
	ds_read_b128 v[178:181], v133 offset:23040
	ds_read_b128 v[182:185], v133 offset:25600
	ds_read_b128 v[186:189], v133 offset:28160
	s_addk_i32 s4, 0x80
	s_setprio 1
	s_waitcnt lgkmcnt(3)
	v_mfma_f32_16x16x32_bf16 v[64:67], v[154:157], v[174:177], v[64:67]
	s_waitcnt lgkmcnt(2)
	v_mfma_f32_16x16x32_bf16 v[68:71], v[154:157], v[178:181], v[68:71]
	s_waitcnt lgkmcnt(1)
	v_mfma_f32_16x16x32_bf16 v[72:75], v[154:157], v[182:185], v[72:75]
	s_waitcnt lgkmcnt(0)
	v_mfma_f32_16x16x32_bf16 v[76:79], v[154:157], v[186:189], v[76:79]
	v_mfma_f32_16x16x32_bf16 v[80:83], v[158:161], v[174:177], v[80:83]
	v_mfma_f32_16x16x32_bf16 v[84:87], v[158:161], v[178:181], v[84:87]
	v_mfma_f32_16x16x32_bf16 v[88:91], v[158:161], v[182:185], v[88:91]
	v_mfma_f32_16x16x32_bf16 v[92:95], v[158:161], v[186:189], v[92:95]
	v_mfma_f32_16x16x32_bf16 v[154:157], v[162:165], v[174:177], v[96:99]
	v_mfma_f32_16x16x32_bf16 v[158:161], v[162:165], v[178:181], v[100:103]
	v_mfma_f32_16x16x32_bf16 v[190:193], v[162:165], v[182:185], v[104:107]
	v_mfma_f32_16x16x32_bf16 v[162:165], v[162:165], v[186:189], v[108:111]
	v_mfma_f32_16x16x32_bf16 v[174:177], v[166:169], v[174:177], v[112:115]
	v_mfma_f32_16x16x32_bf16 v[178:181], v[166:169], v[178:181], v[116:119]
	v_mfma_f32_16x16x32_bf16 v[182:185], v[166:169], v[182:185], v[120:123]
	v_mfma_f32_16x16x32_bf16 v[166:169], v[166:169], v[186:189], v[124:127]
	s_cmp_lg_u32 s34, 0
	s_cbranch_scc1 .Lfv_10
	s_setprio 0
.Lfv_10:
	ds_read_b128 v[96:99], v131 offset:64
	ds_read_b128 v[186:189], v131 offset:2624
	ds_read_b128 v[194:197], v131 offset:5184
	ds_read_b128 v[198:201], v131 offset:7744
	ds_read_b128 v[202:205], v133 offset:20544
	ds_read_b128 v[206:209], v133 offset:23104
	ds_read_b128 v[210:213], v133 offset:25664
	ds_read_b128 v[214:217], v133 offset:28224
	s_setprio 1
	s_waitcnt lgkmcnt(3)
	v_mfma_f32_16x16x32_bf16 v[124:127], v[96:99], v[202:205], v[64:67]
	s_waitcnt lgkmcnt(2)
	v_mfma_f32_16x16x32_bf16 v[120:123], v[96:99], v[206:209], v[68:71]
	s_waitcnt lgkmcnt(1)
	v_mfma_f32_16x16x32_bf16 v[116:119], v[96:99], v[210:213], v[72:75]
	s_waitcnt lgkmcnt(0)
	v_mfma_f32_16x16x32_bf16 v[112:115], v[96:99], v[214:217], v[76:79]
	v_mfma_f32_16x16x32_bf16 v[108:111], v[186:189], v[202:205], v[80:83]
	v_mfma_f32_16x16x32_bf16 v[104:107], v[186:189], v[206:209], v[84:87]
	v_mfma_f32_16x16x32_bf16 v[100:103], v[186:189], v[210:213], v[88:91]
	v_mfma_f32_16x16x32_bf16 v[96:99], v[186:189], v[214:217], v[92:95]
	v_mfma_f32_16x16x32_bf16 v[92:95], v[194:197], v[202:205], v[154:157]
	v_mfma_f32_16x16x32_bf16 v[88:91], v[194:197], v[206:209], v[158:161]
	v_mfma_f32_16x16x32_bf16 v[84:87], v[194:197], v[210:213], v[190:193]
	v_mfma_f32_16x16x32_bf16 v[80:83], v[194:197], v[214:217], v[162:165]
	v_mfma_f32_16x16x32_bf16 v[76:79], v[198:201], v[202:205], v[174:177]
	v_mfma_f32_16x16x32_bf16 v[72:75], v[198:201], v[206:209], v[178:181]
	v_mfma_f32_16x16x32_bf16 v[68:71], v[198:201], v[210:213], v[182:185]
	v_mfma_f32_16x16x32_bf16 v[64:67], v[198:201], v[214:217], v[166:169]
	s_cmp_lg_u32 s34, 0
	s_cbranch_scc1 .Lfv_11
	s_setprio 0
.Lfv_11:
	v_lshl_add_u64 v[138:139], v[138:139], 0, s[12:13]
	v_lshl_add_u64 v[140:141], v[140:141], 0, s[12:13]
	v_lshl_add_u64 v[142:143], v[142:143], 0, s[12:13]
	v_lshl_add_u64 v[144:145], v[144:145], 0, s[12:13]
	v_lshl_add_u64 v[146:147], v[146:147], 0, s[12:13]
	v_lshl_add_u64 v[148:149], v[148:149], 0, s[12:13]
	v_lshl_add_u64 v[150:151], v[150:151], 0, s[12:13]
	s_andn2_b64 vcc, exec, s[0:1]
	v_lshl_add_u64 v[152:153], v[152:153], 0, s[12:13]
	s_cbranch_vccz .LBB0_1602

.Lfv_12:
	ds_read_b128 v[76:79], v131 offset:64
	ds_read_b128 v[92:95], v131 offset:2624
	ds_read_b128 v[202:205], v131 offset:5184
	ds_read_b128 v[210:213], v131 offset:7744
	ds_read_b128 v[214:217], v133 offset:20544
	ds_read_b128 v[220:223], v133 offset:23104
	ds_read_b128 v[224:227], v133 offset:25664
	ds_read_b128 v[228:231], v133 offset:28224
	s_setprio 1
	s_waitcnt lgkmcnt(3)
	v_mfma_f32_16x16x32_bf16 v[64:67], v[76:79], v[214:217], v[124:127]
	s_waitcnt lgkmcnt(2)
	v_mfma_f32_16x16x32_bf16 v[68:71], v[76:79], v[220:223], v[120:123]
	s_waitcnt lgkmcnt(1)
	v_mfma_f32_16x16x32_bf16 v[72:75], v[76:79], v[224:227], v[116:119]
	s_waitcnt lgkmcnt(0)
	v_mfma_f32_16x16x32_bf16 v[76:79], v[76:79], v[228:231], v[112:115]
	v_mfma_f32_16x16x32_bf16 v[80:83], v[92:95], v[214:217], v[108:111]
	v_mfma_f32_16x16x32_bf16 v[84:87], v[92:95], v[220:223], v[104:107]
	v_mfma_f32_16x16x32_bf16 v[88:91], v[92:95], v[224:227], v[100:103]
	v_mfma_f32_16x16x32_bf16 v[92:95], v[92:95], v[228:231], v[96:99]
	v_mfma_f32_16x16x32_bf16 v[96:99], v[202:205], v[214:217], v[174:177]
	v_mfma_f32_16x16x32_bf16 v[100:103], v[202:205], v[220:223], v[178:181]
	v_mfma_f32_16x16x32_bf16 v[104:107], v[202:205], v[224:227], v[206:209]
	v_mfma_f32_16x16x32_bf16 v[108:111], v[202:205], v[228:231], v[182:185]
	v_mfma_f32_16x16x32_bf16 v[112:115], v[210:213], v[214:217], v[190:193]
	v_mfma_f32_16x16x32_bf16 v[116:119], v[210:213], v[220:223], v[194:197]
	v_mfma_f32_16x16x32_bf16 v[120:123], v[210:213], v[224:227], v[198:201]
	v_mfma_f32_16x16x32_bf16 v[124:127], v[210:213], v[228:231], v[186:189]
	s_cmp_lg_u32 s34, 0
	s_cbranch_scc1 .Lfv_13
	s_setprio 0
.Lfv_13:
	s_cmpk_gt_u32 s4, 0x33f
	s_barrier
	ds_write_b128 v130, v[4:7]
	ds_write_b128 v130, v[12:15] offset:20480
	ds_write_b128 v132, v[20:23]
	ds_write_b128 v132, v[28:31] offset:20480
	ds_write_b128 v134, v[36:39]
	ds_write_b128 v134, v[44:47] offset:20480
	ds_write_b128 v136, v[52:55]
	s_waitcnt vmcnt(0)
	ds_write_b128 v136, v[60:63] offset:20480
	s_waitcnt lgkmcnt(0)
	s_barrier
	s_cbranch_scc1 .LBB0_1597
	global_load_dwordx4 v[4:7], v[168:169], off offset:384
	global_load_dwordx4 v[12:15], v[166:167], off offset:384
	global_load_dwordx4 v[20:23], v[164:165], off offset:384
	global_load_dwordx4 v[28:31], v[162:163], off offset:384
	global_load_dwordx4 v[36:39], v[160:161], off offset:384
	global_load_dwordx4 v[44:47], v[158:159], off offset:384
	global_load_dwordx4 v[52:55], v[156:157], off offset:384
	global_load_dwordx4 v[60:63], v[154:155], off offset:384
	s_branch .LBB0_1597

.LBB0_1662:
	s_setprio 0
	s_cmp_lt_i32 s92, 12
	s_cselect_b64 s[0:1], -1, 0
	s_cmp_gt_i32 s93, 11
	s_cselect_b64 s[4:5], -1, 0
	s_and_b64 s[0:1], s[0:1], s[4:5]
	v_readlane_b32 s12, v243, 0
	s_andn2_b64 vcc, exec, s[0:1]
	v_readlane_b32 s20, v243, 8
	v_readlane_b32 s21, v243, 9
	v_readlane_b32 s26, v243, 14
	v_readlane_b32 s27, v243, 15
	v_readlane_b32 s13, v243, 1
	v_readlane_b32 s14, v243, 2
	v_readlane_b32 s15, v243, 3
	v_readlane_b32 s16, v243, 4
	v_readlane_b32 s17, v243, 5
	v_readlane_b32 s18, v243, 6
	v_readlane_b32 s19, v243, 7
	v_readlane_b32 s22, v243, 10
	v_readlane_b32 s23, v243, 11
	v_readlane_b32 s24, v243, 12
	v_readlane_b32 s25, v243, 13
	s_cbranch_vccnz .LBB0_1720
	s_cmpk_gt_i32 s2, 0x41ff
	s_cbranch_scc1 .LBB0_1666
	v_readlane_b32 s4, v242, 1
	v_lshlrev_b32_e32 v0, 4, v218
	v_mov_b32_e32 v1, 0
	v_readlane_b32 s5, v242, 2
	v_readlane_b32 s6, v242, 3
	v_readlane_b32 s7, v242, 4
	v_readlane_b32 s8, v242, 5
	v_readlane_b32 s9, v242, 6
	v_readlane_b32 s10, v242, 7
	v_readlane_b32 s11, v242, 8
	v_readlane_b32 s12, v242, 9
	v_readlane_b32 s13, v242, 10
	v_readlane_b32 s14, v242, 11
	v_readlane_b32 s15, v242, 12
	v_readlane_b32 s16, v242, 13
	v_readlane_b32 s17, v242, 14
	v_readlane_b32 s18, v242, 15
	v_readlane_b32 s19, v242, 16
	v_lshl_add_u64 v[2:3], s[4:5], 0, v[0:1]
	v_readlane_b32 s4, v243, 49
	v_readlane_b32 s18, v243, 63
	v_readlane_b32 s19, v242, 0
	s_waitcnt vmcnt(25)
	v_mov_b32_e32 v6, 0x21000
	v_mov_b32_e32 v7, 0x31000
	v_lshl_add_u64 v[4:5], s[18:19], 0, v[0:1]
	v_mov_b32_e32 v0, 0x10000
	v_mov_b32_e32 v8, 0x42000
	v_mov_b32_e32 v9, 0x52000
	v_mov_b32_e32 v10, 0x63000
	v_mov_b32_e32 v11, 0x73000
	v_mov_b32_e32 v12, 0x358637bd
	s_mov_b32 s0, 0x800000
	v_readlane_b32 s5, v243, 50
	v_readlane_b32 s6, v243, 51
	v_readlane_b32 s7, v243, 52
	v_readlane_b32 s8, v243, 53
	v_readlane_b32 s9, v243, 54
	v_readlane_b32 s10, v243, 55
	v_readlane_b32 s11, v243, 56
	v_readlane_b32 s12, v243, 57
	v_readlane_b32 s13, v243, 58
	v_readlane_b32 s14, v243, 59
	v_readlane_b32 s15, v243, 60
	v_readlane_b32 s16, v243, 61
	v_readlane_b32 s17, v243, 62
